# adaLN task main loop hand-pipelined: rolling 56-load w_ada window, first window issued before silu staging
# baseline (speedup 1.0000x reference)
.LBB0_75:
	s_andn2_b64 vcc, exec, s[4:5]
	s_cbranch_vccnz .LBB0_105
	s_mul_hi_i32 s25, s96, 0x55555556
	s_lshr_b32 s4, s25, 31
	s_add_i32 s25, s25, s4
	s_mul_i32 s4, s25, 3
	v_lshlrev_b32_e32 v2, 2, v1
	s_sub_i32 s24, s96, s4
	v_and_b32_e32 v2, 0x3fc, v2
	v_mov_b32_e32 v19, 0
	s_mul_i32 s24, s24, 48
	s_mov_b32 s26, 0
	v_lshl_add_u32 v22, v2, 1, 0
	v_lshlrev_b32_e32 v20, 2, v2
	v_mov_b32_e32 v21, v19
	s_movk_i32 s27, 0x810
	s_load_dwordx2 s[28:29], s[0:1], 0x50
	s_lshl_b32 s30, s33, 6
	s_lshl_b32 s31, s25, 9
	s_add_u32 s30, s30, s31
	v_lshrrev_b32_e32 v107, 4, v86
	v_and_b32_e32 v108, 15, v86
	v_mul_u32_u24_e32 v107, 0x30000, v107
	v_lshl_add_u32 v107, v108, 2, v107
	v_add_u32_e32 v108, 0x6000, v107
	v_add_u32_e32 v109, 0xc000, v107
	v_add_u32_e32 v110, 0x12000, v107
	v_add_u32_e32 v111, 0x18000, v107
	v_add_u32_e32 v112, 0x1e000, v107
	v_add_u32_e32 v113, 0x24000, v107
	v_add_u32_e32 v114, 0x2a000, v107
	s_waitcnt lgkmcnt(0)
	s_add_u32 s28, s28, s30
	s_addc_u32 s29, s29, 0
	global_load_dword v120, v107, s[28:29]
	global_load_dword v121, v108, s[28:29]
	global_load_dword v122, v109, s[28:29]
	global_load_dword v123, v110, s[28:29]
	global_load_dword v124, v111, s[28:29]
	global_load_dword v125, v112, s[28:29]
	global_load_dword v126, v113, s[28:29]
	global_load_dword v127, v114, s[28:29]
	s_add_u32 s28, s28, 0xc0000
	s_addc_u32 s29, s29, 0
	global_load_dword v128, v107, s[28:29]
	global_load_dword v129, v108, s[28:29]
	global_load_dword v130, v109, s[28:29]
	global_load_dword v131, v110, s[28:29]
	global_load_dword v132, v111, s[28:29]
	global_load_dword v133, v112, s[28:29]
	global_load_dword v134, v113, s[28:29]
	global_load_dword v135, v114, s[28:29]
	s_add_u32 s28, s28, 0xc0000
	s_addc_u32 s29, s29, 0
	global_load_dword v136, v107, s[28:29]
	global_load_dword v137, v108, s[28:29]
	global_load_dword v138, v109, s[28:29]
	global_load_dword v139, v110, s[28:29]
	global_load_dword v140, v111, s[28:29]
	global_load_dword v141, v112, s[28:29]
	global_load_dword v142, v113, s[28:29]
	global_load_dword v143, v114, s[28:29]
	s_add_u32 s28, s28, 0xc0000
	s_addc_u32 s29, s29, 0
	global_load_dword v144, v107, s[28:29]
	global_load_dword v145, v108, s[28:29]
	global_load_dword v146, v109, s[28:29]
	global_load_dword v147, v110, s[28:29]
	global_load_dword v148, v111, s[28:29]
	global_load_dword v149, v112, s[28:29]
	global_load_dword v150, v113, s[28:29]
	global_load_dword v151, v114, s[28:29]
	s_add_u32 s28, s28, 0xc0000
	s_addc_u32 s29, s29, 0
	global_load_dword v152, v107, s[28:29]
	global_load_dword v153, v108, s[28:29]
	global_load_dword v154, v109, s[28:29]
	global_load_dword v155, v110, s[28:29]
	global_load_dword v156, v111, s[28:29]
	global_load_dword v157, v112, s[28:29]
	global_load_dword v158, v113, s[28:29]
	global_load_dword v159, v114, s[28:29]
	s_add_u32 s28, s28, 0xc0000
	s_addc_u32 s29, s29, 0
	global_load_dword v160, v107, s[28:29]
	global_load_dword v161, v108, s[28:29]
	global_load_dword v162, v109, s[28:29]
	global_load_dword v163, v110, s[28:29]
	global_load_dword v164, v111, s[28:29]
	global_load_dword v165, v112, s[28:29]
	global_load_dword v166, v113, s[28:29]
	global_load_dword v167, v114, s[28:29]
	s_add_u32 s28, s28, 0xc0000
	s_addc_u32 s29, s29, 0
	global_load_dword v168, v107, s[28:29]
	global_load_dword v169, v108, s[28:29]
	global_load_dword v170, v109, s[28:29]
	global_load_dword v171, v110, s[28:29]
	global_load_dword v172, v111, s[28:29]
	global_load_dword v173, v112, s[28:29]
	global_load_dword v174, v113, s[28:29]
	global_load_dword v175, v114, s[28:29]
	s_add_u32 s28, s28, 0xc0000
	s_addc_u32 s29, s29, 0
.LBB0_77:
	v_add_u32_e32 v2, s26, v1
	v_ashrrev_i32_e32 v3, 8, v2
	v_add_u32_e32 v4, 0x200, v2
	v_add_u32_e32 v5, 0x400, v2
	v_add_u32_e32 v6, 0x600, v2
	v_add_u32_e32 v7, 0x800, v2
	v_add_u32_e32 v8, 0xa00, v2
	v_add_u32_e32 v9, 0xc00, v2
	v_add_u32_e32 v10, 0xe00, v2
	v_add_u32_e32 v11, 0x1000, v2
	v_add_u32_e32 v12, 0x1200, v2
	v_add_u32_e32 v13, 0x1400, v2
	v_add_u32_e32 v2, 0x1600, v2
	v_add_u32_e32 v14, s24, v3
	v_ashrrev_i32_e32 v4, 8, v4
	v_ashrrev_i32_e32 v5, 8, v5
	v_ashrrev_i32_e32 v6, 8, v6
	v_ashrrev_i32_e32 v7, 8, v7
	v_ashrrev_i32_e32 v8, 8, v8
	v_ashrrev_i32_e32 v9, 8, v9
	v_ashrrev_i32_e32 v10, 8, v10
	v_ashrrev_i32_e32 v11, 8, v11
	v_ashrrev_i32_e32 v2, 8, v2
	v_min_i32_e32 v15, 0x81, v14
	v_ashrrev_i32_e32 v12, 8, v12
	v_mad_i32_i24 v23, v3, s27, v22
	v_add_u32_e32 v16, s24, v4
	v_add_u32_e32 v17, s24, v5
	v_add_u32_e32 v24, s24, v6
	v_add_u32_e32 v25, s24, v7
	v_add_u32_e32 v26, s24, v8
	v_add_u32_e32 v27, s24, v9
	v_add_u32_e32 v28, s24, v10
	v_add_u32_e32 v29, s24, v11
	v_add_u32_e32 v32, s24, v2
	v_mad_i32_i24 v82, v2, s27, v22
	v_add_u32_e32 v2, -2, v15
	v_ashrrev_i32_e32 v3, 31, v15
	v_cmp_gt_i32_e32 vcc, 2, v14
	v_ashrrev_i32_e32 v13, 8, v13
	v_add_u32_e32 v30, s24, v12
	v_mad_i32_i24 v74, v6, s27, v22
	v_mad_i32_i24 v76, v8, s27, v22
	v_mad_i32_i24 v78, v10, s27, v22
	v_mad_i32_i24 v80, v12, s27, v22
	v_min_i32_e32 v6, 0x81, v16
	v_min_i32_e32 v8, 0x81, v17
	v_min_i32_e32 v10, 0x81, v24
	v_min_i32_e32 v12, 0x81, v25
	v_min_i32_e32 v33, 0x81, v26
	v_min_i32_e32 v34, 0x81, v27
	v_min_i32_e32 v35, 0x81, v28
	v_min_i32_e32 v36, 0x81, v29
	v_cndmask_b32_e32 v3, 0, v3, vcc
	v_cndmask_b32_e32 v2, v2, v15, vcc
	s_waitcnt vmcnt(0)
	v_cndmask_b32_e64 v18, 24, 16, vcc
	v_cmp_gt_i32_e32 vcc, 2, v16
	v_add_u32_e32 v31, s24, v13
	v_mad_i32_i24 v72, v4, s27, v22
	v_mad_i32_i24 v73, v5, s27, v22
	v_mad_i32_i24 v77, v9, s27, v22
	v_mad_i32_i24 v79, v11, s27, v22
	v_mad_i32_i24 v81, v13, s27, v22
	v_min_i32_e32 v37, 0x81, v30
	v_add_u32_e32 v9, -2, v6
	v_ashrrev_i32_e32 v11, 31, v8
	v_cmp_gt_i32_e64 s[4:5], 2, v17
	v_add_u32_e32 v13, -2, v8
	v_ashrrev_i32_e32 v14, 31, v10
	v_cmp_gt_i32_e64 s[6:7], 2, v24
	v_add_u32_e32 v15, -2, v10
	v_ashrrev_i32_e32 v16, 31, v12
	v_cmp_gt_i32_e64 s[8:9], 2, v25
	v_add_u32_e32 v17, -2, v12
	v_ashrrev_i32_e32 v24, 31, v33
	v_cmp_gt_i32_e64 s[10:11], 2, v26
	v_add_u32_e32 v25, -2, v33
	v_ashrrev_i32_e32 v26, 31, v34
	v_cmp_gt_i32_e64 s[12:13], 2, v27
	v_add_u32_e32 v27, -2, v34
	v_ashrrev_i32_e32 v40, 31, v35
	v_cmp_gt_i32_e64 s[14:15], 2, v28
	v_add_u32_e32 v28, -2, v35
	v_add_u32_e32 v41, -2, v36
	v_ashrrev_i32_e32 v42, 31, v36
	v_cmp_gt_i32_e64 s[16:17], 2, v29
	v_lshl_add_u64 v[4:5], s[0:1], 0, v[18:19]
	v_cndmask_b32_e64 v18, 24, 16, vcc
	v_mad_i32_i24 v75, v7, s27, v22
	v_min_i32_e32 v39, 0x81, v32
	v_ashrrev_i32_e32 v7, 31, v6
	v_add_u32_e32 v43, -2, v37
	v_ashrrev_i32_e32 v29, 31, v37
	v_cmp_gt_i32_e64 s[18:19], 2, v30
	v_cndmask_b32_e32 v6, v9, v6, vcc
	v_cndmask_b32_e64 v9, 0, v11, s[4:5]
	v_cndmask_b32_e64 v8, v13, v8, s[4:5]
	v_cndmask_b32_e64 v11, 0, v14, s[6:7]
	v_cndmask_b32_e64 v10, v15, v10, s[6:7]
	v_cndmask_b32_e64 v13, 0, v16, s[8:9]
	v_cndmask_b32_e64 v12, v17, v12, s[8:9]
	v_cndmask_b32_e64 v15, 0, v24, s[10:11]
	v_cndmask_b32_e64 v14, v25, v33, s[10:11]
	v_cndmask_b32_e64 v17, 0, v26, s[12:13]
	v_cndmask_b32_e64 v16, v27, v34, s[12:13]
	v_cndmask_b32_e64 v25, 0, v40, s[14:15]
	v_cndmask_b32_e64 v24, v28, v35, s[14:15]
	v_cndmask_b32_e64 v27, 0, v42, s[16:17]
	v_cndmask_b32_e64 v26, v41, v36, s[16:17]
	global_load_dwordx2 v[4:5], v[4:5], off
	v_lshl_add_u64 v[34:35], s[0:1], 0, v[18:19]
	v_cndmask_b32_e64 v18, 24, 16, s[4:5]
	v_add_u32_e32 v45, -2, v39
	v_ashrrev_i32_e32 v46, 31, v39
	v_cmp_gt_i32_e64 s[22:23], 2, v32
	v_cndmask_b32_e64 v29, 0, v29, s[18:19]
	v_cndmask_b32_e64 v28, v43, v37, s[18:19]
	v_lshlrev_b64 v[48:49], 12, v[24:25]
	v_lshlrev_b64 v[52:53], 12, v[26:27]
	global_load_dwordx2 v[24:25], v[34:35], off
	v_lshl_add_u64 v[26:27], s[0:1], 0, v[18:19]
	v_cndmask_b32_e64 v18, 24, 16, s[6:7]
	v_cndmask_b32_e64 v33, 0, v46, s[22:23]
	v_cndmask_b32_e64 v32, v45, v39, s[22:23]
	v_lshlrev_b64 v[54:55], 12, v[28:29]
	global_load_dwordx2 v[28:29], v[26:27], off
	v_lshl_add_u64 v[26:27], s[0:1], 0, v[18:19]
	v_cndmask_b32_e64 v18, 24, 16, s[8:9]
	v_lshlrev_b64 v[58:59], 12, v[32:33]
	global_load_dwordx2 v[32:33], v[26:27], off
	v_lshl_add_u64 v[26:27], s[0:1], 0, v[18:19]
	v_cndmask_b32_e64 v18, 24, 16, s[10:11]
	v_min_i32_e32 v38, 0x81, v31
	global_load_dwordx2 v[36:37], v[26:27], off
	v_lshl_add_u64 v[26:27], s[0:1], 0, v[18:19]
	v_cndmask_b32_e64 v18, 24, 16, s[12:13]
	v_ashrrev_i32_e32 v44, 31, v38
	v_cmp_gt_i32_e64 s[20:21], 2, v31
	global_load_dwordx2 v[40:41], v[26:27], off
	v_lshl_add_u64 v[26:27], s[0:1], 0, v[18:19]
	v_cndmask_b32_e64 v18, 24, 16, s[14:15]
	v_cndmask_b32_e64 v31, 0, v44, s[20:21]
	global_load_dwordx2 v[44:45], v[26:27], off
	v_lshl_add_u64 v[26:27], s[0:1], 0, v[18:19]
	v_cndmask_b32_e64 v18, 24, 16, s[16:17]
	global_load_dwordx2 v[50:51], v[26:27], off
	v_lshl_add_u64 v[26:27], s[0:1], 0, v[18:19]
	v_cndmask_b32_e64 v18, 24, 16, s[18:19]
	global_load_dwordx2 v[60:61], v[26:27], off
	v_lshl_add_u64 v[26:27], s[0:1], 0, v[18:19]
	v_cndmask_b32_e64 v18, 24, 16, s[20:21]
	global_load_dwordx2 v[62:63], v[26:27], off
	v_lshl_add_u64 v[26:27], s[0:1], 0, v[18:19]
	v_cndmask_b32_e64 v18, 24, 16, s[22:23]
	global_load_dwordx2 v[64:65], v[26:27], off
	v_lshl_add_u64 v[26:27], s[0:1], 0, v[18:19]
	global_load_dwordx2 v[66:67], v[26:27], off
	v_lshlrev_b64 v[2:3], 12, v[2:3]
	v_cndmask_b32_e32 v7, 0, v7, vcc
	v_lshlrev_b64 v[6:7], 12, v[6:7]
	v_add_u32_e32 v30, -2, v38
	v_lshlrev_b64 v[8:9], 12, v[8:9]
	v_cndmask_b32_e64 v30, v30, v38, s[20:21]
	v_lshlrev_b64 v[10:11], 12, v[10:11]
	v_lshlrev_b64 v[12:13], 12, v[12:13]
	v_lshlrev_b64 v[56:57], 12, v[30:31]
	v_lshlrev_b64 v[14:15], 12, v[14:15]
	v_lshlrev_b64 v[16:17], 12, v[16:17]
	s_addk_i32 s26, 0x1800
	s_cmpk_eq_i32 s26, 0x3000
	s_waitcnt vmcnt(11)
	v_lshl_add_u64 v[2:3], v[4:5], 0, v[2:3]
	v_lshl_add_u64 v[2:3], v[2:3], 0, v[20:21]
	s_waitcnt vmcnt(10)
	v_lshl_add_u64 v[4:5], v[24:25], 0, v[6:7]
	global_load_dwordx4 v[24:27], v[2:3], off
	v_lshl_add_u64 v[2:3], v[4:5], 0, v[20:21]
	s_waitcnt vmcnt(10)
	v_lshl_add_u64 v[4:5], v[28:29], 0, v[8:9]
	global_load_dwordx4 v[28:31], v[2:3], off
	v_lshl_add_u64 v[2:3], v[4:5], 0, v[20:21]
	s_waitcnt vmcnt(10)
	v_lshl_add_u64 v[4:5], v[32:33], 0, v[10:11]
	global_load_dwordx4 v[32:35], v[2:3], off
	v_lshl_add_u64 v[2:3], v[4:5], 0, v[20:21]
	s_waitcnt vmcnt(10)
	v_lshl_add_u64 v[4:5], v[36:37], 0, v[12:13]
	global_load_dwordx4 v[36:39], v[2:3], off
	v_lshl_add_u64 v[2:3], v[4:5], 0, v[20:21]
	s_waitcnt vmcnt(10)
	v_lshl_add_u64 v[4:5], v[40:41], 0, v[14:15]
	global_load_dwordx4 v[40:43], v[2:3], off
	v_lshl_add_u64 v[2:3], v[4:5], 0, v[20:21]
	s_waitcnt vmcnt(10)
	v_lshl_add_u64 v[4:5], v[44:45], 0, v[16:17]
	global_load_dwordx4 v[44:47], v[2:3], off
	v_lshl_add_u64 v[2:3], v[4:5], 0, v[20:21]
	s_waitcnt vmcnt(10)
	v_lshl_add_u64 v[4:5], v[50:51], 0, v[48:49]
	global_load_dwordx4 v[48:51], v[2:3], off
	v_lshl_add_u64 v[4:5], v[4:5], 0, v[20:21]
	s_waitcnt vmcnt(10)
	v_lshl_add_u64 v[2:3], v[60:61], 0, v[52:53]
	v_lshl_add_u64 v[2:3], v[2:3], 0, v[20:21]
	global_load_dwordx4 v[10:13], v[2:3], off
	s_waitcnt vmcnt(10)
	v_lshl_add_u64 v[6:7], v[62:63], 0, v[54:55]
	global_load_dwordx4 v[52:55], v[4:5], off
	v_lshl_add_u64 v[2:3], v[6:7], 0, v[20:21]
	s_waitcnt vmcnt(10)
	v_lshl_add_u64 v[4:5], v[64:65], 0, v[56:57]
	global_load_dwordx4 v[14:17], v[2:3], off
	s_waitcnt vmcnt(10)
	v_lshl_add_u64 v[56:57], v[66:67], 0, v[58:59]
	v_lshl_add_u64 v[2:3], v[4:5], 0, v[20:21]
	global_load_dwordx4 v[6:9], v[2:3], off
	v_lshl_add_u64 v[2:3], v[56:57], 0, v[20:21]
	global_load_dwordx4 v[2:5], v[2:3], off
	s_waitcnt vmcnt(11)
	v_mul_f32_e32 v18, 0xbfb8aa3b, v24
	v_mul_f32_e32 v56, 0xbfb8aa3b, v25
	v_mul_f32_e32 v57, 0xbfb8aa3b, v26
	v_mul_f32_e32 v58, 0xbfb8aa3b, v27
	v_exp_f32_e32 v18, v18
	v_exp_f32_e32 v56, v56
	v_exp_f32_e32 v57, v57
	v_exp_f32_e32 v58, v58
	s_waitcnt vmcnt(10)
	v_mul_f32_e32 v59, 0xbfb8aa3b, v28
	v_mul_f32_e32 v60, 0xbfb8aa3b, v29
	v_mul_f32_e32 v61, 0xbfb8aa3b, v30
	v_mul_f32_e32 v62, 0xbfb8aa3b, v31
	v_exp_f32_e32 v63, v59
	v_exp_f32_e32 v60, v60
	v_exp_f32_e32 v61, v61
	v_exp_f32_e32 v62, v62
	s_waitcnt vmcnt(9)
	v_mul_f32_e32 v59, 0xbfb8aa3b, v32
	v_mul_f32_e32 v64, 0xbfb8aa3b, v33
	v_mul_f32_e32 v65, 0xbfb8aa3b, v34
	v_mul_f32_e32 v66, 0xbfb8aa3b, v35
	v_exp_f32_e32 v67, v59
	v_exp_f32_e32 v64, v64
	v_exp_f32_e32 v65, v65
	v_exp_f32_e32 v66, v66
	s_waitcnt vmcnt(8)
	v_mul_f32_e32 v59, 0xbfb8aa3b, v36
	v_mul_f32_e32 v68, 0xbfb8aa3b, v37
	v_mul_f32_e32 v69, 0xbfb8aa3b, v38
	v_mul_f32_e32 v70, 0xbfb8aa3b, v39
	v_exp_f32_e32 v71, v59
	v_exp_f32_e32 v68, v68
	v_exp_f32_e32 v69, v69
	v_exp_f32_e32 v70, v70
	s_waitcnt vmcnt(7)
	v_mul_f32_e32 v59, 0xbfb8aa3b, v40
	v_mul_f32_e32 v83, 0xbfb8aa3b, v41
	v_mul_f32_e32 v84, 0xbfb8aa3b, v42
	v_mul_f32_e32 v85, 0xbfb8aa3b, v43
	v_add_f32_e32 v18, 1.0, v18
	v_add_f32_e32 v87, 1.0, v56
	v_add_f32_e32 v88, 1.0, v57
	v_add_f32_e32 v89, 1.0, v58
	v_exp_f32_e32 v90, v59
	v_exp_f32_e32 v83, v83
	v_exp_f32_e32 v84, v84
	v_exp_f32_e32 v85, v85
	s_waitcnt vmcnt(6)
	v_mul_f32_e32 v91, 0xbfb8aa3b, v44
	v_mul_f32_e32 v92, 0xbfb8aa3b, v45
	v_mul_f32_e32 v93, 0xbfb8aa3b, v46
	v_mul_f32_e32 v94, 0xbfb8aa3b, v47
	v_rcp_f32_e32 v56, v18
	v_rcp_f32_e32 v57, v87
	v_rcp_f32_e32 v58, v88
	v_rcp_f32_e32 v59, v89
	v_add_f32_e32 v18, 1.0, v63
	v_add_f32_e32 v63, 1.0, v60
	v_add_f32_e32 v87, 1.0, v61
	v_add_f32_e32 v88, 1.0, v62
	v_exp_f32_e32 v89, v91
	v_exp_f32_e32 v91, v92
	v_exp_f32_e32 v92, v93
	v_exp_f32_e32 v93, v94
	s_waitcnt vmcnt(5)
	v_mul_f32_e32 v94, 0xbfb8aa3b, v48
	v_mul_f32_e32 v95, 0xbfb8aa3b, v49
	v_mul_f32_e32 v96, 0xbfb8aa3b, v50
	v_mul_f32_e32 v97, 0xbfb8aa3b, v51
	v_rcp_f32_e32 v60, v18
	v_rcp_f32_e32 v61, v63
	v_rcp_f32_e32 v62, v87
	v_rcp_f32_e32 v63, v88
	v_add_f32_e32 v18, 1.0, v67
	v_add_f32_e32 v67, 1.0, v64
	v_add_f32_e32 v87, 1.0, v65
	v_add_f32_e32 v88, 1.0, v66
	v_exp_f32_e32 v94, v94
	v_exp_f32_e32 v95, v95
	v_exp_f32_e32 v96, v96
	v_exp_f32_e32 v97, v97
	s_waitcnt vmcnt(3)
	v_mul_f32_e32 v98, 0xbfb8aa3b, v52
	v_mul_f32_e32 v99, 0xbfb8aa3b, v53
	v_rcp_f32_e32 v64, v18
	v_rcp_f32_e32 v65, v67
	v_rcp_f32_e32 v66, v87
	v_rcp_f32_e32 v67, v88
	v_add_f32_e32 v18, 1.0, v71
	v_add_f32_e32 v71, 1.0, v68
	v_add_f32_e32 v87, 1.0, v69
	v_add_f32_e32 v88, 1.0, v70
	v_exp_f32_e32 v98, v98
	v_exp_f32_e32 v99, v99
	v_mul_f32_e32 v102, 0xbfb8aa3b, v10
	v_mul_f32_e32 v103, 0xbfb8aa3b, v11
	v_mul_f32_e32 v104, 0xbfb8aa3b, v12
	v_mul_f32_e32 v105, 0xbfb8aa3b, v13
	v_mul_f32_e32 v100, 0xbfb8aa3b, v54
	v_mul_f32_e32 v101, 0xbfb8aa3b, v55
	v_rcp_f32_e32 v68, v18
	v_rcp_f32_e32 v69, v71
	v_rcp_f32_e32 v70, v87
	v_rcp_f32_e32 v71, v88
	v_add_f32_e32 v18, 1.0, v90
	v_add_f32_e32 v83, 1.0, v83
	v_add_f32_e32 v84, 1.0, v84
	v_add_f32_e32 v85, 1.0, v85
	v_exp_f32_e32 v87, v102
	v_exp_f32_e32 v88, v103
	v_exp_f32_e32 v90, v104
	v_exp_f32_e32 v102, v105
	s_waitcnt vmcnt(2)
	v_mul_f32_e32 v103, 0xbfb8aa3b, v14
	v_mul_f32_e32 v104, 0xbfb8aa3b, v15
	v_mul_f32_e32 v105, 0xbfb8aa3b, v16
	v_mul_f32_e32 v106, 0xbfb8aa3b, v17
	v_exp_f32_e32 v100, v100
	v_exp_f32_e32 v101, v101
	v_pk_mul_f32 v[24:25], v[24:25], v[56:57]
	v_pk_mul_f32 v[26:27], v[26:27], v[58:59]
	v_rcp_f32_e32 v56, v18
	v_rcp_f32_e32 v57, v83
	v_rcp_f32_e32 v58, v84
	v_rcp_f32_e32 v59, v85
	v_add_f32_e32 v18, 1.0, v89
	v_add_f32_e32 v83, 1.0, v91
	v_add_f32_e32 v84, 1.0, v92
	v_add_f32_e32 v85, 1.0, v93
	v_exp_f32_e32 v89, v103
	v_exp_f32_e32 v91, v104
	v_exp_f32_e32 v92, v105
	v_exp_f32_e32 v93, v106
	s_waitcnt vmcnt(1)
	v_mul_f32_e32 v103, 0xbfb8aa3b, v6
	v_mul_f32_e32 v104, 0xbfb8aa3b, v7
	v_mul_f32_e32 v105, 0xbfb8aa3b, v8
	v_mul_f32_e32 v106, 0xbfb8aa3b, v9
	v_pk_mul_f32 v[28:29], v[28:29], v[60:61]
	v_pk_mul_f32 v[30:31], v[30:31], v[62:63]
	v_rcp_f32_e32 v60, v18
	v_rcp_f32_e32 v61, v83
	v_rcp_f32_e32 v62, v84
	v_rcp_f32_e32 v63, v85
	v_add_f32_e32 v18, 1.0, v94
	v_add_f32_e32 v83, 1.0, v95
	v_add_f32_e32 v84, 1.0, v96
	v_add_f32_e32 v85, 1.0, v97
	v_cvt_pk_bf16_f32 v24, v24, v25
	v_cvt_pk_bf16_f32 v25, v26, v27
	v_exp_f32_e32 v94, v103
	v_exp_f32_e32 v95, v104
	v_exp_f32_e32 v96, v105
	v_exp_f32_e32 v97, v106
	s_waitcnt vmcnt(0)
	v_mul_f32_e32 v103, 0xbfb8aa3b, v2
	v_mul_f32_e32 v104, 0xbfb8aa3b, v3
	v_mul_f32_e32 v105, 0xbfb8aa3b, v4
	v_mul_f32_e32 v106, 0xbfb8aa3b, v5
	v_pk_mul_f32 v[26:27], v[32:33], v[64:65]
	v_pk_mul_f32 v[32:33], v[34:35], v[66:67]
	v_rcp_f32_e32 v34, v18
	v_rcp_f32_e32 v35, v83
	v_rcp_f32_e32 v64, v84
	v_rcp_f32_e32 v65, v85
	ds_write_b64 v23, v[24:25]
	v_cvt_pk_bf16_f32 v24, v28, v29
	v_cvt_pk_bf16_f32 v25, v30, v31
	v_add_f32_e32 v18, 1.0, v98
	v_add_f32_e32 v23, 1.0, v99
	v_exp_f32_e32 v83, v103
	v_exp_f32_e32 v84, v104
	v_exp_f32_e32 v85, v105
	v_exp_f32_e32 v98, v106
	v_pk_mul_f32 v[28:29], v[36:37], v[68:69]
	v_pk_mul_f32 v[30:31], v[38:39], v[70:71]
	ds_write_b64 v72, v[24:25]
	v_cvt_pk_bf16_f32 v24, v26, v27
	v_cvt_pk_bf16_f32 v25, v32, v33
	v_rcp_f32_e32 v26, v18
	v_rcp_f32_e32 v27, v23
	v_add_f32_e32 v18, 1.0, v87
	v_add_f32_e32 v23, 1.0, v88
	v_add_f32_e32 v66, 1.0, v100
	v_add_f32_e32 v67, 1.0, v101
	v_pk_mul_f32 v[36:37], v[40:41], v[56:57]
	v_pk_mul_f32 v[38:39], v[42:43], v[58:59]
	ds_write_b64 v73, v[24:25]
	v_cvt_pk_bf16_f32 v24, v28, v29
	v_cvt_pk_bf16_f32 v25, v30, v31
	v_rcp_f32_e32 v28, v18
	v_rcp_f32_e32 v29, v23
	v_add_f32_e32 v18, 1.0, v89
	v_add_f32_e32 v23, 1.0, v91
	v_rcp_f32_e32 v32, v66
	v_rcp_f32_e32 v33, v67
	v_add_f32_e32 v66, 1.0, v90
	v_add_f32_e32 v67, 1.0, v102
	v_pk_mul_f32 v[40:41], v[44:45], v[60:61]
	v_pk_mul_f32 v[42:43], v[46:47], v[62:63]
	ds_write_b64 v74, v[24:25]
	v_cvt_pk_bf16_f32 v24, v36, v37
	v_cvt_pk_bf16_f32 v25, v38, v39
	v_rcp_f32_e32 v36, v18
	v_rcp_f32_e32 v37, v23
	v_add_f32_e32 v18, 1.0, v94
	v_add_f32_e32 v23, 1.0, v95
	v_add_f32_e32 v46, 1.0, v96
	v_add_f32_e32 v47, 1.0, v97
	v_rcp_f32_e32 v30, v66
	v_rcp_f32_e32 v31, v67
	v_add_f32_e32 v56, 1.0, v92
	v_add_f32_e32 v57, 1.0, v93
	v_pk_mul_f32 v[34:35], v[48:49], v[34:35]
	v_pk_mul_f32 v[44:45], v[50:51], v[64:65]
	ds_write_b64 v75, v[24:25]
	v_cvt_pk_bf16_f32 v24, v40, v41
	v_cvt_pk_bf16_f32 v25, v42, v43
	v_rcp_f32_e32 v40, v18
	v_rcp_f32_e32 v41, v23
	v_rcp_f32_e32 v42, v46
	v_rcp_f32_e32 v43, v47
	v_add_f32_e32 v18, 1.0, v83
	v_add_f32_e32 v23, 1.0, v84
	v_add_f32_e32 v46, 1.0, v85
	v_add_f32_e32 v47, 1.0, v98
	v_rcp_f32_e32 v38, v56
	v_rcp_f32_e32 v39, v57
	ds_write_b64 v76, v[24:25]
	v_cvt_pk_bf16_f32 v24, v34, v35
	v_cvt_pk_bf16_f32 v25, v44, v45
	v_rcp_f32_e32 v34, v18
	v_rcp_f32_e32 v35, v23
	v_rcp_f32_e32 v44, v46
	v_rcp_f32_e32 v45, v47
	v_pk_mul_f32 v[26:27], v[52:53], v[26:27]
	v_pk_mul_f32 v[32:33], v[54:55], v[32:33]
	v_pk_mul_f32 v[10:11], v[10:11], v[28:29]
	v_pk_mul_f32 v[12:13], v[12:13], v[30:31]
	ds_write_b64 v77, v[24:25]
	v_cvt_pk_bf16_f32 v24, v26, v27
	v_cvt_pk_bf16_f32 v25, v32, v33
	v_cvt_pk_bf16_f32 v10, v10, v11
	v_cvt_pk_bf16_f32 v11, v12, v13
	v_pk_mul_f32 v[12:13], v[14:15], v[36:37]
	v_pk_mul_f32 v[14:15], v[16:17], v[38:39]
	v_pk_mul_f32 v[6:7], v[6:7], v[40:41]
	v_pk_mul_f32 v[8:9], v[8:9], v[42:43]
	v_pk_mul_f32 v[2:3], v[2:3], v[34:35]
	v_pk_mul_f32 v[4:5], v[4:5], v[44:45]
	ds_write_b64 v78, v[24:25]
	ds_write_b64 v79, v[10:11]
	v_cvt_pk_bf16_f32 v10, v12, v13
	v_cvt_pk_bf16_f32 v11, v14, v15
	v_cvt_pk_bf16_f32 v6, v6, v7
	v_cvt_pk_bf16_f32 v7, v8, v9
	v_cvt_pk_bf16_f32 v2, v2, v3
	v_cvt_pk_bf16_f32 v3, v4, v5
	ds_write_b64 v80, v[10:11]
	ds_write_b64 v81, v[6:7]
	ds_write_b64 v82, v[2:3]
	s_cbranch_scc0 .LBB0_77
	s_lshl_b32 s4, s33, 4
	s_lshl_b32 s5, s25, 7
	s_add_i32 s4, s4, s5
	s_waitcnt lgkmcnt(0)
	s_barrier
	s_ashr_i32 s5, s4, 31
	s_lshl_b64 s[6:7], s[4:5], 2
	v_and_b32_e32 v62, 15, v86
	v_lshrrev_b32_e32 v63, 4, v86
	v_and_b32_e32 v15, 48, v86
	v_mul_u32_u24_e32 v1, 0x810, v62
	v_add_u32_e32 v1, v1, v15
	v_add_u32_e32 v14, 0x10200, v1
	ds_read_b128 v[64:67], v1
	ds_read_b128 v[68:71], v1 offset:33024
	ds_read_b128 v[72:75], v14
	v_mov_b32_e32 v2, 0
	v_mov_b32_e32 v3, 0
	v_mov_b32_e32 v4, 0
	v_mov_b32_e32 v5, 0
	v_mov_b32_e32 v6, 0
	v_mov_b32_e32 v7, 0
	v_mov_b32_e32 v8, 0
	v_mov_b32_e32 v9, 0
	v_mov_b32_e32 v10, 0
	v_mov_b32_e32 v11, 0
	v_mov_b32_e32 v12, 0
	v_mov_b32_e32 v13, 0
	ds_read_b128 v[76:79], v1 offset:64
	ds_read_b128 v[80:83], v1 offset:33088
	ds_read_b128 v[84:87], v14 offset:64
	s_waitcnt vmcnt(48)
	v_cvt_pk_bf16_f32 v176, v120, v121
	v_cvt_pk_bf16_f32 v177, v122, v123
	v_cvt_pk_bf16_f32 v178, v124, v125
	v_cvt_pk_bf16_f32 v179, v126, v127
	global_load_dword v120, v107, s[28:29]
	global_load_dword v121, v108, s[28:29]
	global_load_dword v122, v109, s[28:29]
	global_load_dword v123, v110, s[28:29]
	global_load_dword v124, v111, s[28:29]
	global_load_dword v125, v112, s[28:29]
	global_load_dword v126, v113, s[28:29]
	global_load_dword v127, v114, s[28:29]
	s_add_u32 s28, s28, 0xc0000
	s_addc_u32 s29, s29, 0
	s_waitcnt lgkmcnt(3)
	v_mfma_f32_16x16x32_bf16 v[10:13], v[64:67], v[176:179], v[10:13]
	v_mfma_f32_16x16x32_bf16 v[6:9], v[68:71], v[176:179], v[6:9]
	v_mfma_f32_16x16x32_bf16 v[2:5], v[72:75], v[176:179], v[2:5]
	ds_read_b128 v[64:67], v1 offset:128
	ds_read_b128 v[68:71], v1 offset:33152
	ds_read_b128 v[72:75], v14 offset:128
	s_waitcnt vmcnt(48)
	v_cvt_pk_bf16_f32 v180, v128, v129
	v_cvt_pk_bf16_f32 v181, v130, v131
	v_cvt_pk_bf16_f32 v182, v132, v133
	v_cvt_pk_bf16_f32 v183, v134, v135
	global_load_dword v128, v107, s[28:29]
	global_load_dword v129, v108, s[28:29]
	global_load_dword v130, v109, s[28:29]
	global_load_dword v131, v110, s[28:29]
	global_load_dword v132, v111, s[28:29]
	global_load_dword v133, v112, s[28:29]
	global_load_dword v134, v113, s[28:29]
	global_load_dword v135, v114, s[28:29]
	s_add_u32 s28, s28, 0xc0000
	s_addc_u32 s29, s29, 0
	s_waitcnt lgkmcnt(3)
	v_mfma_f32_16x16x32_bf16 v[10:13], v[76:79], v[180:183], v[10:13]
	v_mfma_f32_16x16x32_bf16 v[6:9], v[80:83], v[180:183], v[6:9]
	v_mfma_f32_16x16x32_bf16 v[2:5], v[84:87], v[180:183], v[2:5]
	ds_read_b128 v[76:79], v1 offset:192
	ds_read_b128 v[80:83], v1 offset:33216
	ds_read_b128 v[84:87], v14 offset:192
	s_waitcnt vmcnt(48)
	v_cvt_pk_bf16_f32 v176, v136, v137
	v_cvt_pk_bf16_f32 v177, v138, v139
	v_cvt_pk_bf16_f32 v178, v140, v141
	v_cvt_pk_bf16_f32 v179, v142, v143
	global_load_dword v136, v107, s[28:29]
	global_load_dword v137, v108, s[28:29]
	global_load_dword v138, v109, s[28:29]
	global_load_dword v139, v110, s[28:29]
	global_load_dword v140, v111, s[28:29]
	global_load_dword v141, v112, s[28:29]
	global_load_dword v142, v113, s[28:29]
	global_load_dword v143, v114, s[28:29]
	s_add_u32 s28, s28, 0xc0000
	s_addc_u32 s29, s29, 0
	s_waitcnt lgkmcnt(3)
	v_mfma_f32_16x16x32_bf16 v[10:13], v[64:67], v[176:179], v[10:13]
	v_mfma_f32_16x16x32_bf16 v[6:9], v[68:71], v[176:179], v[6:9]
	v_mfma_f32_16x16x32_bf16 v[2:5], v[72:75], v[176:179], v[2:5]
	ds_read_b128 v[64:67], v1 offset:256
	ds_read_b128 v[68:71], v1 offset:33280
	ds_read_b128 v[72:75], v14 offset:256
	s_waitcnt vmcnt(48)
	v_cvt_pk_bf16_f32 v180, v144, v145
	v_cvt_pk_bf16_f32 v181, v146, v147
	v_cvt_pk_bf16_f32 v182, v148, v149
	v_cvt_pk_bf16_f32 v183, v150, v151
	global_load_dword v144, v107, s[28:29]
	global_load_dword v145, v108, s[28:29]
	global_load_dword v146, v109, s[28:29]
	global_load_dword v147, v110, s[28:29]
	global_load_dword v148, v111, s[28:29]
	global_load_dword v149, v112, s[28:29]
	global_load_dword v150, v113, s[28:29]
	global_load_dword v151, v114, s[28:29]
	s_add_u32 s28, s28, 0xc0000
	s_addc_u32 s29, s29, 0
	s_waitcnt lgkmcnt(3)
	v_mfma_f32_16x16x32_bf16 v[10:13], v[76:79], v[180:183], v[10:13]
	v_mfma_f32_16x16x32_bf16 v[6:9], v[80:83], v[180:183], v[6:9]
	v_mfma_f32_16x16x32_bf16 v[2:5], v[84:87], v[180:183], v[2:5]
	ds_read_b128 v[76:79], v1 offset:320
	ds_read_b128 v[80:83], v1 offset:33344
	ds_read_b128 v[84:87], v14 offset:320
	s_waitcnt vmcnt(48)
	v_cvt_pk_bf16_f32 v176, v152, v153
	v_cvt_pk_bf16_f32 v177, v154, v155
	v_cvt_pk_bf16_f32 v178, v156, v157
	v_cvt_pk_bf16_f32 v179, v158, v159
	global_load_dword v152, v107, s[28:29]
	global_load_dword v153, v108, s[28:29]
	global_load_dword v154, v109, s[28:29]
	global_load_dword v155, v110, s[28:29]
	global_load_dword v156, v111, s[28:29]
	global_load_dword v157, v112, s[28:29]
	global_load_dword v158, v113, s[28:29]
	global_load_dword v159, v114, s[28:29]
	s_add_u32 s28, s28, 0xc0000
	s_addc_u32 s29, s29, 0
	s_waitcnt lgkmcnt(3)
	v_mfma_f32_16x16x32_bf16 v[10:13], v[64:67], v[176:179], v[10:13]
	v_mfma_f32_16x16x32_bf16 v[6:9], v[68:71], v[176:179], v[6:9]
	v_mfma_f32_16x16x32_bf16 v[2:5], v[72:75], v[176:179], v[2:5]
	ds_read_b128 v[64:67], v1 offset:384
	ds_read_b128 v[68:71], v1 offset:33408
	ds_read_b128 v[72:75], v14 offset:384
	s_waitcnt vmcnt(48)
	v_cvt_pk_bf16_f32 v180, v160, v161
	v_cvt_pk_bf16_f32 v181, v162, v163
	v_cvt_pk_bf16_f32 v182, v164, v165
	v_cvt_pk_bf16_f32 v183, v166, v167
	global_load_dword v160, v107, s[28:29]
	global_load_dword v161, v108, s[28:29]
	global_load_dword v162, v109, s[28:29]
	global_load_dword v163, v110, s[28:29]
	global_load_dword v164, v111, s[28:29]
	global_load_dword v165, v112, s[28:29]
	global_load_dword v166, v113, s[28:29]
	global_load_dword v167, v114, s[28:29]
	s_add_u32 s28, s28, 0xc0000
	s_addc_u32 s29, s29, 0
	s_waitcnt lgkmcnt(3)
	v_mfma_f32_16x16x32_bf16 v[10:13], v[76:79], v[180:183], v[10:13]
	v_mfma_f32_16x16x32_bf16 v[6:9], v[80:83], v[180:183], v[6:9]
	v_mfma_f32_16x16x32_bf16 v[2:5], v[84:87], v[180:183], v[2:5]
	ds_read_b128 v[76:79], v1 offset:448
	ds_read_b128 v[80:83], v1 offset:33472
	ds_read_b128 v[84:87], v14 offset:448
	s_waitcnt vmcnt(48)
	v_cvt_pk_bf16_f32 v176, v168, v169
	v_cvt_pk_bf16_f32 v177, v170, v171
	v_cvt_pk_bf16_f32 v178, v172, v173
	v_cvt_pk_bf16_f32 v179, v174, v175
	global_load_dword v168, v107, s[28:29]
	global_load_dword v169, v108, s[28:29]
	global_load_dword v170, v109, s[28:29]
	global_load_dword v171, v110, s[28:29]
	global_load_dword v172, v111, s[28:29]
	global_load_dword v173, v112, s[28:29]
	global_load_dword v174, v113, s[28:29]
	global_load_dword v175, v114, s[28:29]
	s_add_u32 s28, s28, 0xc0000
	s_addc_u32 s29, s29, 0
	s_waitcnt lgkmcnt(3)
	v_mfma_f32_16x16x32_bf16 v[10:13], v[64:67], v[176:179], v[10:13]
	v_mfma_f32_16x16x32_bf16 v[6:9], v[68:71], v[176:179], v[6:9]
	v_mfma_f32_16x16x32_bf16 v[2:5], v[72:75], v[176:179], v[2:5]
	ds_read_b128 v[64:67], v1 offset:512
	ds_read_b128 v[68:71], v1 offset:33536
	ds_read_b128 v[72:75], v14 offset:512
	s_waitcnt vmcnt(48)
	v_cvt_pk_bf16_f32 v180, v120, v121
	v_cvt_pk_bf16_f32 v181, v122, v123
	v_cvt_pk_bf16_f32 v182, v124, v125
	v_cvt_pk_bf16_f32 v183, v126, v127
	global_load_dword v120, v107, s[28:29]
	global_load_dword v121, v108, s[28:29]
	global_load_dword v122, v109, s[28:29]
	global_load_dword v123, v110, s[28:29]
	global_load_dword v124, v111, s[28:29]
	global_load_dword v125, v112, s[28:29]
	global_load_dword v126, v113, s[28:29]
	global_load_dword v127, v114, s[28:29]
	s_add_u32 s28, s28, 0xc0000
	s_addc_u32 s29, s29, 0
	s_waitcnt lgkmcnt(3)
	v_mfma_f32_16x16x32_bf16 v[10:13], v[76:79], v[180:183], v[10:13]
	v_mfma_f32_16x16x32_bf16 v[6:9], v[80:83], v[180:183], v[6:9]
	v_mfma_f32_16x16x32_bf16 v[2:5], v[84:87], v[180:183], v[2:5]
	ds_read_b128 v[76:79], v1 offset:576
	ds_read_b128 v[80:83], v1 offset:33600
	ds_read_b128 v[84:87], v14 offset:576
	s_waitcnt vmcnt(48)
	v_cvt_pk_bf16_f32 v176, v128, v129
	v_cvt_pk_bf16_f32 v177, v130, v131
	v_cvt_pk_bf16_f32 v178, v132, v133
	v_cvt_pk_bf16_f32 v179, v134, v135
	global_load_dword v128, v107, s[28:29]
	global_load_dword v129, v108, s[28:29]
	global_load_dword v130, v109, s[28:29]
	global_load_dword v131, v110, s[28:29]
	global_load_dword v132, v111, s[28:29]
	global_load_dword v133, v112, s[28:29]
	global_load_dword v134, v113, s[28:29]
	global_load_dword v135, v114, s[28:29]
	s_add_u32 s28, s28, 0xc0000
	s_addc_u32 s29, s29, 0
	s_waitcnt lgkmcnt(3)
	v_mfma_f32_16x16x32_bf16 v[10:13], v[64:67], v[176:179], v[10:13]
	v_mfma_f32_16x16x32_bf16 v[6:9], v[68:71], v[176:179], v[6:9]
	v_mfma_f32_16x16x32_bf16 v[2:5], v[72:75], v[176:179], v[2:5]
	ds_read_b128 v[64:67], v1 offset:640
	ds_read_b128 v[68:71], v1 offset:33664
	ds_read_b128 v[72:75], v14 offset:640
	s_waitcnt vmcnt(48)
	v_cvt_pk_bf16_f32 v180, v136, v137
	v_cvt_pk_bf16_f32 v181, v138, v139
	v_cvt_pk_bf16_f32 v182, v140, v141
	v_cvt_pk_bf16_f32 v183, v142, v143
	global_load_dword v136, v107, s[28:29]
	global_load_dword v137, v108, s[28:29]
	global_load_dword v138, v109, s[28:29]
	global_load_dword v139, v110, s[28:29]
	global_load_dword v140, v111, s[28:29]
	global_load_dword v141, v112, s[28:29]
	global_load_dword v142, v113, s[28:29]
	global_load_dword v143, v114, s[28:29]
	s_add_u32 s28, s28, 0xc0000
	s_addc_u32 s29, s29, 0
	s_waitcnt lgkmcnt(3)
	v_mfma_f32_16x16x32_bf16 v[10:13], v[76:79], v[180:183], v[10:13]
	v_mfma_f32_16x16x32_bf16 v[6:9], v[80:83], v[180:183], v[6:9]
	v_mfma_f32_16x16x32_bf16 v[2:5], v[84:87], v[180:183], v[2:5]
	ds_read_b128 v[76:79], v1 offset:704
	ds_read_b128 v[80:83], v1 offset:33728
	ds_read_b128 v[84:87], v14 offset:704
	s_waitcnt vmcnt(48)
	v_cvt_pk_bf16_f32 v176, v144, v145
	v_cvt_pk_bf16_f32 v177, v146, v147
	v_cvt_pk_bf16_f32 v178, v148, v149
	v_cvt_pk_bf16_f32 v179, v150, v151
	global_load_dword v144, v107, s[28:29]
	global_load_dword v145, v108, s[28:29]
	global_load_dword v146, v109, s[28:29]
	global_load_dword v147, v110, s[28:29]
	global_load_dword v148, v111, s[28:29]
	global_load_dword v149, v112, s[28:29]
	global_load_dword v150, v113, s[28:29]
	global_load_dword v151, v114, s[28:29]
	s_add_u32 s28, s28, 0xc0000
	s_addc_u32 s29, s29, 0
	s_waitcnt lgkmcnt(3)
	v_mfma_f32_16x16x32_bf16 v[10:13], v[64:67], v[176:179], v[10:13]
	v_mfma_f32_16x16x32_bf16 v[6:9], v[68:71], v[176:179], v[6:9]
	v_mfma_f32_16x16x32_bf16 v[2:5], v[72:75], v[176:179], v[2:5]
	ds_read_b128 v[64:67], v1 offset:768
	ds_read_b128 v[68:71], v1 offset:33792
	ds_read_b128 v[72:75], v14 offset:768
	s_waitcnt vmcnt(48)
	v_cvt_pk_bf16_f32 v180, v152, v153
	v_cvt_pk_bf16_f32 v181, v154, v155
	v_cvt_pk_bf16_f32 v182, v156, v157
	v_cvt_pk_bf16_f32 v183, v158, v159
	global_load_dword v152, v107, s[28:29]
	global_load_dword v153, v108, s[28:29]
	global_load_dword v154, v109, s[28:29]
	global_load_dword v155, v110, s[28:29]
	global_load_dword v156, v111, s[28:29]
	global_load_dword v157, v112, s[28:29]
	global_load_dword v158, v113, s[28:29]
	global_load_dword v159, v114, s[28:29]
	s_add_u32 s28, s28, 0xc0000
	s_addc_u32 s29, s29, 0
	s_waitcnt lgkmcnt(3)
	v_mfma_f32_16x16x32_bf16 v[10:13], v[76:79], v[180:183], v[10:13]
	v_mfma_f32_16x16x32_bf16 v[6:9], v[80:83], v[180:183], v[6:9]
	v_mfma_f32_16x16x32_bf16 v[2:5], v[84:87], v[180:183], v[2:5]
	ds_read_b128 v[76:79], v1 offset:832
	ds_read_b128 v[80:83], v1 offset:33856
	ds_read_b128 v[84:87], v14 offset:832
	s_waitcnt vmcnt(48)
	v_cvt_pk_bf16_f32 v176, v160, v161
	v_cvt_pk_bf16_f32 v177, v162, v163
	v_cvt_pk_bf16_f32 v178, v164, v165
	v_cvt_pk_bf16_f32 v179, v166, v167
	global_load_dword v160, v107, s[28:29]
	global_load_dword v161, v108, s[28:29]
	global_load_dword v162, v109, s[28:29]
	global_load_dword v163, v110, s[28:29]
	global_load_dword v164, v111, s[28:29]
	global_load_dword v165, v112, s[28:29]
	global_load_dword v166, v113, s[28:29]
	global_load_dword v167, v114, s[28:29]
	s_add_u32 s28, s28, 0xc0000
	s_addc_u32 s29, s29, 0
	s_waitcnt lgkmcnt(3)
	v_mfma_f32_16x16x32_bf16 v[10:13], v[64:67], v[176:179], v[10:13]
	v_mfma_f32_16x16x32_bf16 v[6:9], v[68:71], v[176:179], v[6:9]
	v_mfma_f32_16x16x32_bf16 v[2:5], v[72:75], v[176:179], v[2:5]
	ds_read_b128 v[64:67], v1 offset:896
	ds_read_b128 v[68:71], v1 offset:33920
	ds_read_b128 v[72:75], v14 offset:896
	s_waitcnt vmcnt(48)
	v_cvt_pk_bf16_f32 v180, v168, v169
	v_cvt_pk_bf16_f32 v181, v170, v171
	v_cvt_pk_bf16_f32 v182, v172, v173
	v_cvt_pk_bf16_f32 v183, v174, v175
	global_load_dword v168, v107, s[28:29]
	global_load_dword v169, v108, s[28:29]
	global_load_dword v170, v109, s[28:29]
	global_load_dword v171, v110, s[28:29]
	global_load_dword v172, v111, s[28:29]
	global_load_dword v173, v112, s[28:29]
	global_load_dword v174, v113, s[28:29]
	global_load_dword v175, v114, s[28:29]
	s_add_u32 s28, s28, 0xc0000
	s_addc_u32 s29, s29, 0
	s_waitcnt lgkmcnt(3)
	v_mfma_f32_16x16x32_bf16 v[10:13], v[76:79], v[180:183], v[10:13]
	v_mfma_f32_16x16x32_bf16 v[6:9], v[80:83], v[180:183], v[6:9]
	v_mfma_f32_16x16x32_bf16 v[2:5], v[84:87], v[180:183], v[2:5]
	ds_read_b128 v[76:79], v1 offset:960
	ds_read_b128 v[80:83], v1 offset:33984
	ds_read_b128 v[84:87], v14 offset:960
	s_waitcnt vmcnt(48)
	v_cvt_pk_bf16_f32 v176, v120, v121
	v_cvt_pk_bf16_f32 v177, v122, v123
	v_cvt_pk_bf16_f32 v178, v124, v125
	v_cvt_pk_bf16_f32 v179, v126, v127
	global_load_dword v120, v107, s[28:29]
	global_load_dword v121, v108, s[28:29]
	global_load_dword v122, v109, s[28:29]
	global_load_dword v123, v110, s[28:29]
	global_load_dword v124, v111, s[28:29]
	global_load_dword v125, v112, s[28:29]
	global_load_dword v126, v113, s[28:29]
	global_load_dword v127, v114, s[28:29]
	s_add_u32 s28, s28, 0xc0000
	s_addc_u32 s29, s29, 0
	s_waitcnt lgkmcnt(3)
	v_mfma_f32_16x16x32_bf16 v[10:13], v[64:67], v[176:179], v[10:13]
	v_mfma_f32_16x16x32_bf16 v[6:9], v[68:71], v[176:179], v[6:9]
	v_mfma_f32_16x16x32_bf16 v[2:5], v[72:75], v[176:179], v[2:5]
	ds_read_b128 v[64:67], v1 offset:1024
	ds_read_b128 v[68:71], v1 offset:34048
	ds_read_b128 v[72:75], v14 offset:1024
	s_waitcnt vmcnt(48)
	v_cvt_pk_bf16_f32 v180, v128, v129
	v_cvt_pk_bf16_f32 v181, v130, v131
	v_cvt_pk_bf16_f32 v182, v132, v133
	v_cvt_pk_bf16_f32 v183, v134, v135
	global_load_dword v128, v107, s[28:29]
	global_load_dword v129, v108, s[28:29]
	global_load_dword v130, v109, s[28:29]
	global_load_dword v131, v110, s[28:29]
	global_load_dword v132, v111, s[28:29]
	global_load_dword v133, v112, s[28:29]
	global_load_dword v134, v113, s[28:29]
	global_load_dword v135, v114, s[28:29]
	s_add_u32 s28, s28, 0xc0000
	s_addc_u32 s29, s29, 0
	s_waitcnt lgkmcnt(3)
	v_mfma_f32_16x16x32_bf16 v[10:13], v[76:79], v[180:183], v[10:13]
	v_mfma_f32_16x16x32_bf16 v[6:9], v[80:83], v[180:183], v[6:9]
	v_mfma_f32_16x16x32_bf16 v[2:5], v[84:87], v[180:183], v[2:5]
	ds_read_b128 v[76:79], v1 offset:1088
	ds_read_b128 v[80:83], v1 offset:34112
	ds_read_b128 v[84:87], v14 offset:1088
	s_waitcnt vmcnt(48)
	v_cvt_pk_bf16_f32 v176, v136, v137
	v_cvt_pk_bf16_f32 v177, v138, v139
	v_cvt_pk_bf16_f32 v178, v140, v141
	v_cvt_pk_bf16_f32 v179, v142, v143
	global_load_dword v136, v107, s[28:29]
	global_load_dword v137, v108, s[28:29]
	global_load_dword v138, v109, s[28:29]
	global_load_dword v139, v110, s[28:29]
	global_load_dword v140, v111, s[28:29]
	global_load_dword v141, v112, s[28:29]
	global_load_dword v142, v113, s[28:29]
	global_load_dword v143, v114, s[28:29]
	s_add_u32 s28, s28, 0xc0000
	s_addc_u32 s29, s29, 0
	s_waitcnt lgkmcnt(3)
	v_mfma_f32_16x16x32_bf16 v[10:13], v[64:67], v[176:179], v[10:13]
	v_mfma_f32_16x16x32_bf16 v[6:9], v[68:71], v[176:179], v[6:9]
	v_mfma_f32_16x16x32_bf16 v[2:5], v[72:75], v[176:179], v[2:5]
	ds_read_b128 v[64:67], v1 offset:1152
	ds_read_b128 v[68:71], v1 offset:34176
	ds_read_b128 v[72:75], v14 offset:1152
	s_waitcnt vmcnt(48)
	v_cvt_pk_bf16_f32 v180, v144, v145
	v_cvt_pk_bf16_f32 v181, v146, v147
	v_cvt_pk_bf16_f32 v182, v148, v149
	v_cvt_pk_bf16_f32 v183, v150, v151
	global_load_dword v144, v107, s[28:29]
	global_load_dword v145, v108, s[28:29]
	global_load_dword v146, v109, s[28:29]
	global_load_dword v147, v110, s[28:29]
	global_load_dword v148, v111, s[28:29]
	global_load_dword v149, v112, s[28:29]
	global_load_dword v150, v113, s[28:29]
	global_load_dword v151, v114, s[28:29]
	s_add_u32 s28, s28, 0xc0000
	s_addc_u32 s29, s29, 0
	s_waitcnt lgkmcnt(3)
	v_mfma_f32_16x16x32_bf16 v[10:13], v[76:79], v[180:183], v[10:13]
	v_mfma_f32_16x16x32_bf16 v[6:9], v[80:83], v[180:183], v[6:9]
	v_mfma_f32_16x16x32_bf16 v[2:5], v[84:87], v[180:183], v[2:5]
	ds_read_b128 v[76:79], v1 offset:1216
	ds_read_b128 v[80:83], v1 offset:34240
	ds_read_b128 v[84:87], v14 offset:1216
	s_waitcnt vmcnt(48)
	v_cvt_pk_bf16_f32 v176, v152, v153
	v_cvt_pk_bf16_f32 v177, v154, v155
	v_cvt_pk_bf16_f32 v178, v156, v157
	v_cvt_pk_bf16_f32 v179, v158, v159
	global_load_dword v152, v107, s[28:29]
	global_load_dword v153, v108, s[28:29]
	global_load_dword v154, v109, s[28:29]
	global_load_dword v155, v110, s[28:29]
	global_load_dword v156, v111, s[28:29]
	global_load_dword v157, v112, s[28:29]
	global_load_dword v158, v113, s[28:29]
	global_load_dword v159, v114, s[28:29]
	s_add_u32 s28, s28, 0xc0000
	s_addc_u32 s29, s29, 0
	s_waitcnt lgkmcnt(3)
	v_mfma_f32_16x16x32_bf16 v[10:13], v[64:67], v[176:179], v[10:13]
	v_mfma_f32_16x16x32_bf16 v[6:9], v[68:71], v[176:179], v[6:9]
	v_mfma_f32_16x16x32_bf16 v[2:5], v[72:75], v[176:179], v[2:5]
	ds_read_b128 v[64:67], v1 offset:1280
	ds_read_b128 v[68:71], v1 offset:34304
	ds_read_b128 v[72:75], v14 offset:1280
	s_waitcnt vmcnt(48)
	v_cvt_pk_bf16_f32 v180, v160, v161
	v_cvt_pk_bf16_f32 v181, v162, v163
	v_cvt_pk_bf16_f32 v182, v164, v165
	v_cvt_pk_bf16_f32 v183, v166, v167
	global_load_dword v160, v107, s[28:29]
	global_load_dword v161, v108, s[28:29]
	global_load_dword v162, v109, s[28:29]
	global_load_dword v163, v110, s[28:29]
	global_load_dword v164, v111, s[28:29]
	global_load_dword v165, v112, s[28:29]
	global_load_dword v166, v113, s[28:29]
	global_load_dword v167, v114, s[28:29]
	s_add_u32 s28, s28, 0xc0000
	s_addc_u32 s29, s29, 0
	s_waitcnt lgkmcnt(3)
	v_mfma_f32_16x16x32_bf16 v[10:13], v[76:79], v[180:183], v[10:13]
	v_mfma_f32_16x16x32_bf16 v[6:9], v[80:83], v[180:183], v[6:9]
	v_mfma_f32_16x16x32_bf16 v[2:5], v[84:87], v[180:183], v[2:5]
	ds_read_b128 v[76:79], v1 offset:1344
	ds_read_b128 v[80:83], v1 offset:34368
	ds_read_b128 v[84:87], v14 offset:1344
	s_waitcnt vmcnt(48)
	v_cvt_pk_bf16_f32 v176, v168, v169
	v_cvt_pk_bf16_f32 v177, v170, v171
	v_cvt_pk_bf16_f32 v178, v172, v173
	v_cvt_pk_bf16_f32 v179, v174, v175
	global_load_dword v168, v107, s[28:29]
	global_load_dword v169, v108, s[28:29]
	global_load_dword v170, v109, s[28:29]
	global_load_dword v171, v110, s[28:29]
	global_load_dword v172, v111, s[28:29]
	global_load_dword v173, v112, s[28:29]
	global_load_dword v174, v113, s[28:29]
	global_load_dword v175, v114, s[28:29]
	s_add_u32 s28, s28, 0xc0000
	s_addc_u32 s29, s29, 0
	s_waitcnt lgkmcnt(3)
	v_mfma_f32_16x16x32_bf16 v[10:13], v[64:67], v[176:179], v[10:13]
	v_mfma_f32_16x16x32_bf16 v[6:9], v[68:71], v[176:179], v[6:9]
	v_mfma_f32_16x16x32_bf16 v[2:5], v[72:75], v[176:179], v[2:5]
	ds_read_b128 v[64:67], v1 offset:1408
	ds_read_b128 v[68:71], v1 offset:34432
	ds_read_b128 v[72:75], v14 offset:1408
	s_waitcnt vmcnt(48)
	v_cvt_pk_bf16_f32 v180, v120, v121
	v_cvt_pk_bf16_f32 v181, v122, v123
	v_cvt_pk_bf16_f32 v182, v124, v125
	v_cvt_pk_bf16_f32 v183, v126, v127
	global_load_dword v120, v107, s[28:29]
	global_load_dword v121, v108, s[28:29]
	global_load_dword v122, v109, s[28:29]
	global_load_dword v123, v110, s[28:29]
	global_load_dword v124, v111, s[28:29]
	global_load_dword v125, v112, s[28:29]
	global_load_dword v126, v113, s[28:29]
	global_load_dword v127, v114, s[28:29]
	s_add_u32 s28, s28, 0xc0000
	s_addc_u32 s29, s29, 0
	s_waitcnt lgkmcnt(3)
	v_mfma_f32_16x16x32_bf16 v[10:13], v[76:79], v[180:183], v[10:13]
	v_mfma_f32_16x16x32_bf16 v[6:9], v[80:83], v[180:183], v[6:9]
	v_mfma_f32_16x16x32_bf16 v[2:5], v[84:87], v[180:183], v[2:5]
	ds_read_b128 v[76:79], v1 offset:1472
	ds_read_b128 v[80:83], v1 offset:34496
	ds_read_b128 v[84:87], v14 offset:1472
	s_waitcnt vmcnt(48)
	v_cvt_pk_bf16_f32 v176, v128, v129
	v_cvt_pk_bf16_f32 v177, v130, v131
	v_cvt_pk_bf16_f32 v178, v132, v133
	v_cvt_pk_bf16_f32 v179, v134, v135
	global_load_dword v128, v107, s[28:29]
	global_load_dword v129, v108, s[28:29]
	global_load_dword v130, v109, s[28:29]
	global_load_dword v131, v110, s[28:29]
	global_load_dword v132, v111, s[28:29]
	global_load_dword v133, v112, s[28:29]
	global_load_dword v134, v113, s[28:29]
	global_load_dword v135, v114, s[28:29]
	s_add_u32 s28, s28, 0xc0000
	s_addc_u32 s29, s29, 0
	s_waitcnt lgkmcnt(3)
	v_mfma_f32_16x16x32_bf16 v[10:13], v[64:67], v[176:179], v[10:13]
	v_mfma_f32_16x16x32_bf16 v[6:9], v[68:71], v[176:179], v[6:9]
	v_mfma_f32_16x16x32_bf16 v[2:5], v[72:75], v[176:179], v[2:5]
	ds_read_b128 v[64:67], v1 offset:1536
	ds_read_b128 v[68:71], v1 offset:34560
	ds_read_b128 v[72:75], v14 offset:1536
	s_waitcnt vmcnt(48)
	v_cvt_pk_bf16_f32 v180, v136, v137
	v_cvt_pk_bf16_f32 v181, v138, v139
	v_cvt_pk_bf16_f32 v182, v140, v141
	v_cvt_pk_bf16_f32 v183, v142, v143
	global_load_dword v136, v107, s[28:29]
	global_load_dword v137, v108, s[28:29]
	global_load_dword v138, v109, s[28:29]
	global_load_dword v139, v110, s[28:29]
	global_load_dword v140, v111, s[28:29]
	global_load_dword v141, v112, s[28:29]
	global_load_dword v142, v113, s[28:29]
	global_load_dword v143, v114, s[28:29]
	s_add_u32 s28, s28, 0xc0000
	s_addc_u32 s29, s29, 0
	s_waitcnt lgkmcnt(3)
	v_mfma_f32_16x16x32_bf16 v[10:13], v[76:79], v[180:183], v[10:13]
	v_mfma_f32_16x16x32_bf16 v[6:9], v[80:83], v[180:183], v[6:9]
	v_mfma_f32_16x16x32_bf16 v[2:5], v[84:87], v[180:183], v[2:5]
	ds_read_b128 v[76:79], v1 offset:1600
	ds_read_b128 v[80:83], v1 offset:34624
	ds_read_b128 v[84:87], v14 offset:1600
	s_waitcnt vmcnt(48)
	v_cvt_pk_bf16_f32 v176, v144, v145
	v_cvt_pk_bf16_f32 v177, v146, v147
	v_cvt_pk_bf16_f32 v178, v148, v149
	v_cvt_pk_bf16_f32 v179, v150, v151
	global_load_dword v144, v107, s[28:29]
	global_load_dword v145, v108, s[28:29]
	global_load_dword v146, v109, s[28:29]
	global_load_dword v147, v110, s[28:29]
	global_load_dword v148, v111, s[28:29]
	global_load_dword v149, v112, s[28:29]
	global_load_dword v150, v113, s[28:29]
	global_load_dword v151, v114, s[28:29]
	s_add_u32 s28, s28, 0xc0000
	s_addc_u32 s29, s29, 0
	s_waitcnt lgkmcnt(3)
	v_mfma_f32_16x16x32_bf16 v[10:13], v[64:67], v[176:179], v[10:13]
	v_mfma_f32_16x16x32_bf16 v[6:9], v[68:71], v[176:179], v[6:9]
	v_mfma_f32_16x16x32_bf16 v[2:5], v[72:75], v[176:179], v[2:5]
	ds_read_b128 v[64:67], v1 offset:1664
	ds_read_b128 v[68:71], v1 offset:34688
	ds_read_b128 v[72:75], v14 offset:1664
	s_waitcnt vmcnt(48)
	v_cvt_pk_bf16_f32 v180, v152, v153
	v_cvt_pk_bf16_f32 v181, v154, v155
	v_cvt_pk_bf16_f32 v182, v156, v157
	v_cvt_pk_bf16_f32 v183, v158, v159
	s_nop 1
	s_waitcnt lgkmcnt(3)
	v_mfma_f32_16x16x32_bf16 v[10:13], v[76:79], v[180:183], v[10:13]
	v_mfma_f32_16x16x32_bf16 v[6:9], v[80:83], v[180:183], v[6:9]
	v_mfma_f32_16x16x32_bf16 v[2:5], v[84:87], v[180:183], v[2:5]
	ds_read_b128 v[76:79], v1 offset:1728
	ds_read_b128 v[80:83], v1 offset:34752
	ds_read_b128 v[84:87], v14 offset:1728
	s_waitcnt vmcnt(40)
	v_cvt_pk_bf16_f32 v176, v160, v161
	v_cvt_pk_bf16_f32 v177, v162, v163
	v_cvt_pk_bf16_f32 v178, v164, v165
	v_cvt_pk_bf16_f32 v179, v166, v167
	s_nop 1
	s_waitcnt lgkmcnt(3)
	v_mfma_f32_16x16x32_bf16 v[10:13], v[64:67], v[176:179], v[10:13]
	v_mfma_f32_16x16x32_bf16 v[6:9], v[68:71], v[176:179], v[6:9]
	v_mfma_f32_16x16x32_bf16 v[2:5], v[72:75], v[176:179], v[2:5]
	ds_read_b128 v[64:67], v1 offset:1792
	ds_read_b128 v[68:71], v1 offset:34816
	ds_read_b128 v[72:75], v14 offset:1792
	s_waitcnt vmcnt(32)
	v_cvt_pk_bf16_f32 v180, v168, v169
	v_cvt_pk_bf16_f32 v181, v170, v171
	v_cvt_pk_bf16_f32 v182, v172, v173
	v_cvt_pk_bf16_f32 v183, v174, v175
	s_nop 1
	s_waitcnt lgkmcnt(3)
	v_mfma_f32_16x16x32_bf16 v[10:13], v[76:79], v[180:183], v[10:13]
	v_mfma_f32_16x16x32_bf16 v[6:9], v[80:83], v[180:183], v[6:9]
	v_mfma_f32_16x16x32_bf16 v[2:5], v[84:87], v[180:183], v[2:5]
	ds_read_b128 v[76:79], v1 offset:1856
	ds_read_b128 v[80:83], v1 offset:34880
	ds_read_b128 v[84:87], v14 offset:1856
	s_waitcnt vmcnt(24)
	v_cvt_pk_bf16_f32 v176, v120, v121
	v_cvt_pk_bf16_f32 v177, v122, v123
	v_cvt_pk_bf16_f32 v178, v124, v125
	v_cvt_pk_bf16_f32 v179, v126, v127
	s_nop 1
	s_waitcnt lgkmcnt(3)
	v_mfma_f32_16x16x32_bf16 v[10:13], v[64:67], v[176:179], v[10:13]
	v_mfma_f32_16x16x32_bf16 v[6:9], v[68:71], v[176:179], v[6:9]
	v_mfma_f32_16x16x32_bf16 v[2:5], v[72:75], v[176:179], v[2:5]
	ds_read_b128 v[64:67], v1 offset:1920
	ds_read_b128 v[68:71], v1 offset:34944
	ds_read_b128 v[72:75], v14 offset:1920
	s_waitcnt vmcnt(16)
	v_cvt_pk_bf16_f32 v180, v128, v129
	v_cvt_pk_bf16_f32 v181, v130, v131
	v_cvt_pk_bf16_f32 v182, v132, v133
	v_cvt_pk_bf16_f32 v183, v134, v135
	s_nop 1
	s_waitcnt lgkmcnt(3)
	v_mfma_f32_16x16x32_bf16 v[10:13], v[76:79], v[180:183], v[10:13]
	v_mfma_f32_16x16x32_bf16 v[6:9], v[80:83], v[180:183], v[6:9]
	v_mfma_f32_16x16x32_bf16 v[2:5], v[84:87], v[180:183], v[2:5]
	ds_read_b128 v[76:79], v1 offset:1984
	ds_read_b128 v[80:83], v1 offset:35008
	ds_read_b128 v[84:87], v14 offset:1984
	s_waitcnt vmcnt(8)
	v_cvt_pk_bf16_f32 v176, v136, v137
	v_cvt_pk_bf16_f32 v177, v138, v139
	v_cvt_pk_bf16_f32 v178, v140, v141
	v_cvt_pk_bf16_f32 v179, v142, v143
	s_nop 1
	s_waitcnt lgkmcnt(3)
	v_mfma_f32_16x16x32_bf16 v[10:13], v[64:67], v[176:179], v[10:13]
	v_mfma_f32_16x16x32_bf16 v[6:9], v[68:71], v[176:179], v[6:9]
	v_mfma_f32_16x16x32_bf16 v[2:5], v[72:75], v[176:179], v[2:5]
	s_waitcnt vmcnt(0)
	v_cvt_pk_bf16_f32 v180, v144, v145
	v_cvt_pk_bf16_f32 v181, v146, v147
	v_cvt_pk_bf16_f32 v182, v148, v149
	v_cvt_pk_bf16_f32 v183, v150, v151
	s_nop 1
	s_waitcnt lgkmcnt(0)
	v_mfma_f32_16x16x32_bf16 v[10:13], v[76:79], v[180:183], v[10:13]
	v_mfma_f32_16x16x32_bf16 v[6:9], v[80:83], v[180:183], v[6:9]
	v_mfma_f32_16x16x32_bf16 v[2:5], v[84:87], v[180:183], v[2:5]
	s_nop 7
	s_load_dwordx2 s[8:9], s[0:1], 0x58
	v_or_b32_e32 v14, s4, v62
	v_ashrrev_i32_e32 v15, 31, v14
	s_add_u32 s4, s74, s6
	s_addc_u32 s5, s75, s7
	s_waitcnt lgkmcnt(0)
	v_lshl_add_u64 v[14:15], v[14:15], 2, s[8:9]
	global_load_dword v16, v[14:15], off
	v_lshlrev_b32_e32 v14, 2, v62
	v_mov_b32_e32 v15, 0
	v_lshl_or_b32 v1, v63, 2, s24
	v_lshl_add_u64 v[14:15], s[4:5], 0, v[14:15]
	s_mov_b64 s[4:5], 0x2380000
	s_movk_i32 s6, 0x82
	v_lshl_add_u64 v[14:15], v[14:15], 0, s[4:5]
	v_cmp_gt_i32_e32 vcc, s6, v1
	s_and_saveexec_b64 s[4:5], vcc
	s_cbranch_execz .LBB0_82
	s_movk_i32 s7, 0x6000
	v_mul_lo_u32 v18, v1, s7
	v_ashrrev_i32_e32 v19, 31, v18
	s_waitcnt vmcnt(0)
	v_add_f32_e32 v10, v10, v16
	v_lshl_add_u64 v[18:19], v[14:15], 0, v[18:19]
	global_store_dword v[18:19], v10, off
